# stack of the bit-exact small edits on v99: lazy lane-half exchange in softmax, permlane swaps in the projection epilogues, init next-tile prefetch, 64-byte aligned loop heads
# baseline (speedup 1.0000x reference)
; #define AT_GLOADK(k0) do { kreg = *(const u32x4*)(Kb + (size_t)((k0) + (tid >> 3)) * 64 + (tid & 7) * 8); \
;             if (MLA) preg = *(const u32x2*)(Pb + (size_t)((k0) + (tid >> 3)) * 32 + (tid & 7) * 4); } while (0)
; #define AT_GLOADV(k0) do { vreg = *(const u32x4*)(Vb + (size_t)((k0) + (tid >> 3)) * 64 + (tid & 7) * 8); } while (0)
; #define AT_WRITEK(buf) do { *(LAS u32x4*)(lds + (buf) * KBUF + (tid >> 3) * KSTR + (tid & 7) * 16) = kreg; \
;             if (MLA) *(LAS u32x2*)(lds + (buf) * KBUF + (tid >> 3) * KSTR + 128 + (tid & 7) * 8) = preg; } while (0)
; #define AT_WRITEV(buf) do { *(LAS u32x4*)(lds + 2 * KBUF + (buf) * VBUF + (tid >> 3) * VSTR + (tid & 7) * 16) = vreg; } while (0)
; template <bool MLA>
; DI void attn_phase(const int TID, const int BID, LAS unsigned char* lds, const Params& p, bool need_ctx) {
;     ...
;         AT_GLOADK(0); AT_GLOADV(0); AT_WRITEK(0); AT_WRITEV(0);
;         AT_GLOADK(64); AT_WRITEK(1);
;         __syncthreads();
;         AT_QK(sa0, sa1, 0);
;         __syncthreads();
.Lamla_prio:
	ds_read_b128 v[136:139], v243 offset:0
	ds_read_b128 v[140:143], v243 offset:6656
	ds_read_b128 v[144:147], v243 offset:32
	ds_read_b128 v[148:151], v243 offset:6688
	s_waitcnt lgkmcnt(3)
	v_mfma_f32_32x32x16_bf16 v[32:47], v[136:139], v[112:115], 0
	ds_read_b128 v[136:139], v243 offset:64
	s_waitcnt lgkmcnt(3)
	v_mfma_f32_32x32x16_bf16 v[48:63], v[140:143], v[112:115], 0
	ds_read_b128 v[140:143], v243 offset:6720
	s_waitcnt lgkmcnt(3)
	v_mfma_f32_32x32x16_bf16 v[32:47], v[144:147], v[116:119], v[32:47]
	ds_read_b128 v[144:147], v243 offset:96
	s_waitcnt lgkmcnt(3)
	v_mfma_f32_32x32x16_bf16 v[48:63], v[148:151], v[116:119], v[48:63]
	ds_read_b128 v[148:151], v243 offset:6752
	s_waitcnt lgkmcnt(3)
	v_mfma_f32_32x32x16_bf16 v[32:47], v[136:139], v[120:123], v[32:47]
	ds_read_b128 v[136:139], v243 offset:128
	s_waitcnt lgkmcnt(3)
	v_mfma_f32_32x32x16_bf16 v[48:63], v[140:143], v[120:123], v[48:63]
	ds_read_b128 v[140:143], v243 offset:6784
	s_waitcnt lgkmcnt(3)
	v_mfma_f32_32x32x16_bf16 v[32:47], v[144:147], v[124:127], v[32:47]
	ds_read_b128 v[144:147], v243 offset:160
	s_waitcnt lgkmcnt(3)
	v_mfma_f32_32x32x16_bf16 v[48:63], v[148:151], v[124:127], v[48:63]
	ds_read_b128 v[148:151], v243 offset:6816
	s_waitcnt lgkmcnt(3)
	v_mfma_f32_32x32x16_bf16 v[32:47], v[136:139], v[128:131], v[32:47]
	s_waitcnt lgkmcnt(2)
	v_mfma_f32_32x32x16_bf16 v[48:63], v[140:143], v[128:131], v[48:63]
	s_waitcnt lgkmcnt(1)
	v_mfma_f32_32x32x16_bf16 v[32:47], v[144:147], v[132:135], v[32:47]
	s_waitcnt lgkmcnt(0)
	v_mfma_f32_32x32x16_bf16 v[48:63], v[148:151], v[132:135], v[48:63]
	s_waitcnt lgkmcnt(0)
	s_nop 7
	s_barrier
	ds_read_b128 v[136:139], v243 offset:13312
	ds_read_b128 v[140:143], v243 offset:19968
	ds_read_b128 v[144:147], v243 offset:13344
	ds_read_b128 v[148:151], v243 offset:20000
	v_max3_f32 v168, v32, v33, v34
	v_max3_f32 v170, v48, v49, v50
	v_max3_f32 v168, v168, v35, v36
	v_max3_f32 v170, v170, v51, v52
	v_max3_f32 v168, v168, v37, v38
	v_max3_f32 v170, v170, v53, v54
	v_max3_f32 v168, v168, v39, v40
	v_max3_f32 v170, v170, v55, v56
	v_max3_f32 v168, v168, v41, v42
	v_max3_f32 v170, v170, v57, v58
	v_max3_f32 v168, v168, v43, v44
	v_max3_f32 v170, v170, v59, v60
	v_max3_f32 v168, v168, v45, v46
	v_max3_f32 v170, v170, v61, v62
	v_max3_f32 v168, v168, v170, v47
	v_max_f32_e32 v168, v168, v63
	v_mov_b32_e32 v170, v168
	s_nop 1
	v_permlane32_swap_b32_e32 v168, v170
	v_max_f32_e32 v168, v168, v170
	v_mov_b32_e32 v170, v168
	v_sub_f32_e32 v218, v218, v170
	v_sub_f32_e32 v219, v219, v170
	v_sub_f32_e32 v220, v220, v170
	v_sub_f32_e32 v221, v221, v170
	v_sub_f32_e32 v222, v222, v170
	v_sub_f32_e32 v223, v223, v170
	v_sub_f32_e32 v224, v224, v170
	v_sub_f32_e32 v225, v225, v170
	v_sub_f32_e32 v226, v226, v170
	v_sub_f32_e32 v227, v227, v170
	v_sub_f32_e32 v228, v228, v170
	v_sub_f32_e32 v229, v229, v170
	v_sub_f32_e32 v230, v230, v170
	v_sub_f32_e32 v231, v231, v170
	v_sub_f32_e32 v232, v232, v170
	v_sub_f32_e32 v233, v233, v170
	v_sub_f32_e32 v32, v32, v170
	v_sub_f32_e32 v33, v33, v170
	v_sub_f32_e32 v34, v34, v170
	v_sub_f32_e32 v35, v35, v170
	v_sub_f32_e32 v36, v36, v170
	v_sub_f32_e32 v37, v37, v170
	v_sub_f32_e32 v38, v38, v170
	v_sub_f32_e32 v39, v39, v170
	v_sub_f32_e32 v40, v40, v170
	v_sub_f32_e32 v41, v41, v170
	v_sub_f32_e32 v42, v42, v170
	v_sub_f32_e32 v43, v43, v170
	v_sub_f32_e32 v44, v44, v170
	v_sub_f32_e32 v45, v45, v170
	v_sub_f32_e32 v46, v46, v170
	v_sub_f32_e32 v47, v47, v170
	v_sub_f32_e32 v48, v48, v170
	v_sub_f32_e32 v49, v49, v170
	v_sub_f32_e32 v50, v50, v170
	v_sub_f32_e32 v51, v51, v170
	v_sub_f32_e32 v52, v52, v170
	v_sub_f32_e32 v53, v53, v170
	v_sub_f32_e32 v54, v54, v170
	v_sub_f32_e32 v55, v55, v170
	v_sub_f32_e32 v56, v56, v170
	v_sub_f32_e32 v57, v57, v170
	v_sub_f32_e32 v58, v58, v170
	v_sub_f32_e32 v59, v59, v170
	v_sub_f32_e32 v60, v60, v170
	v_sub_f32_e32 v61, v61, v170
	v_sub_f32_e32 v62, v62, v170
	v_sub_f32_e32 v63, v63, v170
	s_waitcnt lgkmcnt(3)
	v_mfma_f32_32x32x16_bf16 v[64:79], v[136:139], v[112:115], v[218:233]
	v_exp_f32_e32 v32, v32
	v_exp_f32_e32 v48, v48
	v_exp_f32_e32 v33, v33
	v_exp_f32_e32 v49, v49
	v_exp_f32_e32 v34, v34
	ds_read_b128 v[136:139], v243 offset:13376
	s_mov_b32 s55, s52
	s_mov_b32 s52, s53
	s_mov_b32 s53, s54
	s_mov_b32 s54, s55
	s_mov_b32 s9, 0
	s_waitcnt lgkmcnt(3)
	v_mfma_f32_32x32x16_bf16 v[80:95], v[140:143], v[112:115], v[218:233]
	v_exp_f32_e32 v50, v50
	v_cvt_pk_bf16_f32 v96, v32, v33
	v_cvt_pk_bf16_f32 v104, v48, v49
	v_exp_f32_e32 v35, v35
	v_exp_f32_e32 v51, v51
	ds_read_b128 v[140:143], v243 offset:20032
	global_load_dwordx4 v[208:211], v167, s[2:3]
	global_load_dwordx2 v[216:217], v165, s[10:11]
	global_load_dwordx4 v[212:215], v167, s[4:5]
	s_add_u32 s2, s2, 0x2000
	s_addc_u32 s3, s3, 0
	s_add_u32 s10, s10, 0x1000
	s_addc_u32 s11, s11, 0
	s_add_u32 s4, s4, 0x2000
	s_addc_u32 s5, s5, 0
	v_add_u32_e32 v163, s53, v240
	v_add_u32_e32 v164, s54, v241
	s_waitcnt lgkmcnt(3)
	v_mfma_f32_32x32x16_bf16 v[64:79], v[144:147], v[116:119], v[64:79]
	v_exp_f32_e32 v36, v36
	v_exp_f32_e32 v52, v52
	v_cvt_pk_bf16_f32 v97, v34, v35
	v_cvt_pk_bf16_f32 v105, v50, v51
	v_exp_f32_e32 v37, v37
	ds_read_b128 v[144:147], v243 offset:13408
	s_waitcnt lgkmcnt(3)
	v_mfma_f32_32x32x16_bf16 v[80:95], v[148:151], v[116:119], v[80:95]
	v_exp_f32_e32 v53, v53
	v_exp_f32_e32 v38, v38
	v_exp_f32_e32 v54, v54
	v_cvt_pk_bf16_f32 v98, v36, v37
	ds_read_b128 v[148:151], v243 offset:20064
	s_waitcnt lgkmcnt(3)
	v_mfma_f32_32x32x16_bf16 v[64:79], v[136:139], v[120:123], v[64:79]
	v_cvt_pk_bf16_f32 v106, v52, v53
	v_exp_f32_e32 v39, v39
	v_exp_f32_e32 v55, v55
	v_exp_f32_e32 v40, v40
	v_exp_f32_e32 v56, v56
	ds_read_b128 v[136:139], v243 offset:13440
	s_waitcnt lgkmcnt(3)
	v_mfma_f32_32x32x16_bf16 v[80:95], v[140:143], v[120:123], v[80:95]
	v_cvt_pk_bf16_f32 v99, v38, v39
	v_cvt_pk_bf16_f32 v107, v54, v55
	v_exp_f32_e32 v41, v41
	v_exp_f32_e32 v57, v57
	v_exp_f32_e32 v42, v42
	ds_read_b128 v[140:143], v243 offset:20096
	s_waitcnt lgkmcnt(3)
	v_mfma_f32_32x32x16_bf16 v[64:79], v[144:147], v[124:127], v[64:79]
	v_exp_f32_e32 v58, v58
	v_cvt_pk_bf16_f32 v100, v40, v41
	v_cvt_pk_bf16_f32 v108, v56, v57
	v_exp_f32_e32 v43, v43
	v_exp_f32_e32 v59, v59
	ds_read_b128 v[144:147], v243 offset:13472
	ds_read_b64_tr_b16 v[176:177], v163 offset:0
	ds_read_b64_tr_b16 v[178:179], v163 offset:1536
	s_waitcnt vmcnt(5)
	ds_write_b128 v238, v[152:155]
	s_waitcnt vmcnt(4)
	ds_write_b64 v239, v[160:161]
	s_waitcnt vmcnt(3)
	ds_write_b128 v164, v[156:159]
	s_waitcnt lgkmcnt(8)
	v_mfma_f32_32x32x16_bf16 v[80:95], v[148:151], v[124:127], v[80:95]
	v_exp_f32_e32 v44, v44
	v_exp_f32_e32 v60, v60
	v_cvt_pk_bf16_f32 v101, v42, v43
	v_cvt_pk_bf16_f32 v109, v58, v59
	v_exp_f32_e32 v45, v45
	ds_read_b128 v[148:151], v243 offset:20128
	ds_read_b64_tr_b16 v[180:181], v163 offset:64
	ds_read_b64_tr_b16 v[182:183], v163 offset:1600
	s_waitcnt lgkmcnt(10)
	v_mfma_f32_32x32x16_bf16 v[64:79], v[136:139], v[128:131], v[64:79]
	v_exp_f32_e32 v61, v61
	v_exp_f32_e32 v46, v46
	v_exp_f32_e32 v62, v62
	v_cvt_pk_bf16_f32 v102, v44, v45
	v_cvt_pk_bf16_f32 v110, v60, v61
	ds_read_b64_tr_b16 v[184:185], v163 offset:6144
	ds_read_b64_tr_b16 v[186:187], v163 offset:7680
	s_waitcnt lgkmcnt(11)
	v_mfma_f32_32x32x16_bf16 v[80:95], v[140:143], v[128:131], v[80:95]
	v_exp_f32_e32 v47, v47
	v_exp_f32_e32 v63, v63
	v_cvt_pk_bf16_f32 v103, v46, v47
	v_cvt_pk_bf16_f32 v111, v62, v63
	ds_read_b64_tr_b16 v[188:189], v163 offset:6208
	ds_read_b64_tr_b16 v[190:191], v163 offset:7744
	s_waitcnt lgkmcnt(12)
	v_mfma_f32_32x32x16_bf16 v[64:79], v[144:147], v[132:135], v[64:79]
	s_waitcnt lgkmcnt(6)
	v_mfma_f32_32x32x16_bf16 v[80:95], v[148:151], v[132:135], v[80:95]
	s_nop 13
	s_waitcnt lgkmcnt(0)
	s_barrier
	s_cmp_eq_u32 s7, 0
	s_cbranch_scc1 .Lamla_tail
	.p2alignl 6, 3212836864

; #define AT_GLOADK(k0) do { kreg = *(const u32x4*)(Kb + (size_t)((k0) + (tid >> 3)) * 64 + (tid & 7) * 8); \
;             if (MLA) preg = *(const u32x2*)(Pb + (size_t)((k0) + (tid >> 3)) * 32 + (tid & 7) * 4); } while (0)
; #define AT_GLOADV(k0) do { vreg = *(const u32x4*)(Vb + (size_t)((k0) + (tid >> 3)) * 64 + (tid & 7) * 8); } while (0)
; #define AT_WRITEK(buf) do { *(LAS u32x4*)(lds + (buf) * KBUF + (tid >> 3) * KSTR + (tid & 7) * 16) = kreg; \
;             if (MLA) *(LAS u32x2*)(lds + (buf) * KBUF + (tid >> 3) * KSTR + 128 + (tid & 7) * 8) = preg; } while (0)
; #define AT_WRITEV(buf) do { *(LAS u32x4*)(lds + 2 * KBUF + (buf) * VBUF + (tid >> 3) * VSTR + (tid & 7) * 16) = vreg; } while (0)
; template <bool MLA>
; DI void attn_phase(const int TID, const int BID, LAS unsigned char* lds, const Params& p, bool need_ctx) {
;     ...
;         f32x16 o0, o1, sa0, sa1, sb0, sb1;
; #pragma unroll
;         for (int j = 0; j < 16; ++j) { o0[j] = 0.f; o1[j] = 0.f; }
;         float mrun = -1e30f, lsum = 0.f;
;         if (wid >= 4) __builtin_amdgcn_s_setprio(1);
;         const int ntile = nk >> 6;
;         AT_GLOADK(0); AT_GLOADV(0); AT_WRITEK(0); AT_WRITEV(0);
;         AT_GLOADK(64); AT_WRITEK(1);
;         __syncthreads();
;         AT_QK(sa0, sa1, 0);
;         __syncthreads();
.Lagqa_prio:
	ds_read_b128 v[136:139], v243 offset:0
	ds_read_b128 v[140:143], v243 offset:4608
	ds_read_b128 v[144:147], v243 offset:32
	ds_read_b128 v[148:151], v243 offset:4640
	s_waitcnt lgkmcnt(3)
	v_mfma_f32_32x32x16_bf16 v[32:47], v[136:139], v[112:115], 0
	ds_read_b128 v[136:139], v243 offset:64
	s_waitcnt lgkmcnt(3)
	v_mfma_f32_32x32x16_bf16 v[48:63], v[140:143], v[112:115], 0
	ds_read_b128 v[140:143], v243 offset:4672
	s_waitcnt lgkmcnt(3)
	v_mfma_f32_32x32x16_bf16 v[32:47], v[144:147], v[116:119], v[32:47]
	ds_read_b128 v[144:147], v243 offset:96
	s_waitcnt lgkmcnt(3)
	v_mfma_f32_32x32x16_bf16 v[48:63], v[148:151], v[116:119], v[48:63]
	ds_read_b128 v[148:151], v243 offset:4704
	s_waitcnt lgkmcnt(3)
	v_mfma_f32_32x32x16_bf16 v[32:47], v[136:139], v[120:123], v[32:47]
	s_waitcnt lgkmcnt(2)
	v_mfma_f32_32x32x16_bf16 v[48:63], v[140:143], v[120:123], v[48:63]
	s_waitcnt lgkmcnt(1)
	v_mfma_f32_32x32x16_bf16 v[32:47], v[144:147], v[124:127], v[32:47]
	s_waitcnt lgkmcnt(0)
	v_mfma_f32_32x32x16_bf16 v[48:63], v[148:151], v[124:127], v[48:63]
	s_waitcnt lgkmcnt(0)
	s_nop 7
	s_barrier
	ds_read_b128 v[136:139], v243 offset:9216
	ds_read_b128 v[140:143], v243 offset:13824
	ds_read_b128 v[144:147], v243 offset:9248
	ds_read_b128 v[148:151], v243 offset:13856
	v_max3_f32 v168, v32, v33, v34
	v_max3_f32 v170, v48, v49, v50
	v_max3_f32 v168, v168, v35, v36
	v_max3_f32 v170, v170, v51, v52
	v_max3_f32 v168, v168, v37, v38
	v_max3_f32 v170, v170, v53, v54
	v_max3_f32 v168, v168, v39, v40
	v_max3_f32 v170, v170, v55, v56
	v_max3_f32 v168, v168, v41, v42
	v_max3_f32 v170, v170, v57, v58
	v_max3_f32 v168, v168, v43, v44
	v_max3_f32 v170, v170, v59, v60
	v_max3_f32 v168, v168, v45, v46
	v_max3_f32 v170, v170, v61, v62
	v_max3_f32 v168, v168, v170, v47
	v_max_f32_e32 v168, v168, v63
	v_mov_b32_e32 v170, v168
	s_nop 1
	v_permlane32_swap_b32_e32 v168, v170
	v_max_f32_e32 v168, v168, v170
	v_mov_b32_e32 v170, v168
	v_sub_f32_e32 v218, v218, v170
	v_sub_f32_e32 v219, v219, v170
	v_sub_f32_e32 v220, v220, v170
	v_sub_f32_e32 v221, v221, v170
	v_sub_f32_e32 v222, v222, v170
	v_sub_f32_e32 v223, v223, v170
	v_sub_f32_e32 v224, v224, v170
	v_sub_f32_e32 v225, v225, v170
	v_sub_f32_e32 v226, v226, v170
	v_sub_f32_e32 v227, v227, v170
	v_sub_f32_e32 v228, v228, v170
	v_sub_f32_e32 v229, v229, v170
	v_sub_f32_e32 v230, v230, v170
	v_sub_f32_e32 v231, v231, v170
	v_sub_f32_e32 v232, v232, v170
	v_sub_f32_e32 v233, v233, v170
	v_sub_f32_e32 v32, v32, v170
	v_sub_f32_e32 v33, v33, v170
	v_sub_f32_e32 v34, v34, v170
	v_sub_f32_e32 v35, v35, v170
	v_sub_f32_e32 v36, v36, v170
	v_sub_f32_e32 v37, v37, v170
	v_sub_f32_e32 v38, v38, v170
	v_sub_f32_e32 v39, v39, v170
	v_sub_f32_e32 v40, v40, v170
	v_sub_f32_e32 v41, v41, v170
	v_sub_f32_e32 v42, v42, v170
	v_sub_f32_e32 v43, v43, v170
	v_sub_f32_e32 v44, v44, v170
	v_sub_f32_e32 v45, v45, v170
	v_sub_f32_e32 v46, v46, v170
	v_sub_f32_e32 v47, v47, v170
	v_sub_f32_e32 v48, v48, v170
	v_sub_f32_e32 v49, v49, v170
	v_sub_f32_e32 v50, v50, v170
	v_sub_f32_e32 v51, v51, v170
	v_sub_f32_e32 v52, v52, v170
	v_sub_f32_e32 v53, v53, v170
	v_sub_f32_e32 v54, v54, v170
	v_sub_f32_e32 v55, v55, v170
	v_sub_f32_e32 v56, v56, v170
	v_sub_f32_e32 v57, v57, v170
	v_sub_f32_e32 v58, v58, v170
	v_sub_f32_e32 v59, v59, v170
	v_sub_f32_e32 v60, v60, v170
	v_sub_f32_e32 v61, v61, v170
	v_sub_f32_e32 v62, v62, v170
	v_sub_f32_e32 v63, v63, v170
	s_waitcnt lgkmcnt(3)
	v_mfma_f32_32x32x16_bf16 v[64:79], v[136:139], v[112:115], v[218:233]
	v_exp_f32_e32 v32, v32
	v_exp_f32_e32 v48, v48
	v_exp_f32_e32 v33, v33
	v_exp_f32_e32 v49, v49
	v_exp_f32_e32 v34, v34
	v_exp_f32_e32 v50, v50
	v_cvt_pk_bf16_f32 v96, v32, v33
	ds_read_b128 v[136:139], v243 offset:9280
	s_mov_b32 s55, s52
	s_mov_b32 s52, s53
	s_mov_b32 s53, s54
	s_mov_b32 s54, s55
	s_mov_b32 s9, 0
	s_waitcnt lgkmcnt(3)
	v_mfma_f32_32x32x16_bf16 v[80:95], v[140:143], v[112:115], v[218:233]
	v_cvt_pk_bf16_f32 v104, v48, v49
	v_exp_f32_e32 v35, v35
	v_exp_f32_e32 v51, v51
	v_exp_f32_e32 v36, v36
	v_exp_f32_e32 v52, v52
	v_cvt_pk_bf16_f32 v97, v34, v35
	v_cvt_pk_bf16_f32 v105, v50, v51
	v_exp_f32_e32 v37, v37
	ds_read_b128 v[140:143], v243 offset:13888
	global_load_dwordx4 v[208:211], v167, s[2:3]
	global_load_dwordx4 v[212:215], v167, s[4:5]
	s_add_u32 s2, s2, 0x2000
	s_addc_u32 s3, s3, 0
	s_add_u32 s4, s4, 0x2000
	s_addc_u32 s5, s5, 0
	v_add_u32_e32 v163, s53, v240
	v_add_u32_e32 v164, s54, v241
	s_waitcnt lgkmcnt(3)
	v_mfma_f32_32x32x16_bf16 v[64:79], v[144:147], v[116:119], v[64:79]
	v_exp_f32_e32 v53, v53
	v_exp_f32_e32 v38, v38
	v_exp_f32_e32 v54, v54
	v_cvt_pk_bf16_f32 v98, v36, v37
	v_cvt_pk_bf16_f32 v106, v52, v53
	v_exp_f32_e32 v39, v39
	v_exp_f32_e32 v55, v55
	ds_read_b128 v[144:147], v243 offset:9312
	ds_read_b64_tr_b16 v[176:177], v163 offset:0
	ds_read_b64_tr_b16 v[178:179], v163 offset:1536
	s_waitcnt lgkmcnt(5)
	v_mfma_f32_32x32x16_bf16 v[80:95], v[148:151], v[116:119], v[80:95]
	v_exp_f32_e32 v40, v40
	v_exp_f32_e32 v56, v56
	v_cvt_pk_bf16_f32 v99, v38, v39
	v_cvt_pk_bf16_f32 v107, v54, v55
	v_exp_f32_e32 v41, v41
	v_exp_f32_e32 v57, v57
	v_exp_f32_e32 v42, v42
	ds_read_b128 v[148:151], v243 offset:13920
	ds_read_b64_tr_b16 v[180:181], v163 offset:64
	ds_read_b64_tr_b16 v[182:183], v163 offset:1600
	s_waitcnt lgkmcnt(7)
	v_mfma_f32_32x32x16_bf16 v[64:79], v[136:139], v[120:123], v[64:79]
	v_exp_f32_e32 v58, v58
	v_cvt_pk_bf16_f32 v100, v40, v41
	v_cvt_pk_bf16_f32 v108, v56, v57
	v_exp_f32_e32 v43, v43
	v_exp_f32_e32 v59, v59
	v_exp_f32_e32 v44, v44
	v_exp_f32_e32 v60, v60
	ds_read_b64_tr_b16 v[184:185], v163 offset:6144
	ds_read_b64_tr_b16 v[186:187], v163 offset:7680
	s_waitcnt vmcnt(3)
	ds_write_b128 v238, v[152:155]
	s_waitcnt vmcnt(2)
	ds_write_b128 v164, v[156:159]
	s_waitcnt lgkmcnt(10)
	v_mfma_f32_32x32x16_bf16 v[80:95], v[140:143], v[120:123], v[80:95]
	v_cvt_pk_bf16_f32 v101, v42, v43
	v_cvt_pk_bf16_f32 v109, v58, v59
	v_exp_f32_e32 v45, v45
	v_exp_f32_e32 v61, v61
	v_exp_f32_e32 v46, v46
	v_exp_f32_e32 v62, v62
	v_cvt_pk_bf16_f32 v102, v44, v45
	v_cvt_pk_bf16_f32 v110, v60, v61
	ds_read_b64_tr_b16 v[188:189], v163 offset:6208
	ds_read_b64_tr_b16 v[190:191], v163 offset:7744
	s_waitcnt lgkmcnt(11)
	v_mfma_f32_32x32x16_bf16 v[64:79], v[144:147], v[124:127], v[64:79]
	v_exp_f32_e32 v47, v47
	v_exp_f32_e32 v63, v63
	v_cvt_pk_bf16_f32 v103, v46, v47
	v_cvt_pk_bf16_f32 v111, v62, v63
	s_waitcnt lgkmcnt(8)
	v_mfma_f32_32x32x16_bf16 v[80:95], v[148:151], v[124:127], v[80:95]
	s_nop 13
	s_waitcnt lgkmcnt(2)
	s_waitcnt lgkmcnt(0)
	s_barrier
	s_cmp_eq_u32 s7, 0
	s_cbranch_scc1 .Lagqa_tail
	.p2alignl 6, 3212836864
